# P1 EpiZ rewritten by hand: PS rows and gain quads loaded up front, QK-norm on raw accumulators with merged scale factors
# baseline (speedup 1.0000x reference)
; __device__ __forceinline__ unsigned cvtpk(float lo, float hi) { f32x2 v = {lo, hi}; bf16x2_t b = __builtin_convertvector(v, bf16x2_t); return __builtin_bit_cast(unsigned, b); }
;     __device__ __forceinline__ void operator()(const f32x4 (&acc)[2][2][4][2], const Unit& u, int wr, int wc, int fr, int fq) const {
;         const bool nrm = (normmask >> u.pn) & 1u;
;         f32x4 gv[2][2];
; #pragma unroll
;         for (int bj = 0; bj < 2; ++bj)
; #pragma unroll
;             for (int n = 0; n < 2; ++n) gv[bj][n] = nrm ? *(const f32x4*)(gtab + u.pn * 64 + 32 * bj + 8 * fq + 4 * n) : (f32x4){1.f, 1.f, 1.f, 1.f};
; #pragma unroll
;         for (int ai = 0; ai < 2; ++ai)
; #pragma unroll
;             for (int m = 0; m < 4; ++m) {
;                 const int row = u.pm * BM + ai * HALF + wr * 64 + m * 16 + fr;
;                 float rs = 1.f;
;                 if (PS) { const f32x4 p = *(const f32x4*)(PS + (size_t)row * 16 + 4 * fq); float s = (p[0] + p[1]) + (p[2] + p[3]); s = bfly_add<16>(s); s = bfly_add<32>(s); rs = rsqrtf(s * (1.f / DM) + EPS); }
;                 f32x4 v[2][2]; float ss = 0.f;
; #pragma unroll
;                 for (int bj = 0; bj < 2; ++bj)
; #pragma unroll
;                     for (int n = 0; n < 2; ++n) { v[bj][n] = acc[ai][bj][m][n] * rs; const f32x4 x = v[bj][n]; ss += (x[0] * x[0] + x[1] * x[1]) + (x[2] * x[2] + x[3] * x[3]); }
;                 if (nrm) { ss = bfly_add<16>(ss); ss = bfly_add<32>(ss); const float r2 = rsqrtf(ss * (1.f / 64.f) + EPS);
; #pragma unroll
;                     for (int bj = 0; bj < 2; ++bj)
; #pragma unroll
;                         for (int n = 0; n < 2; ++n) v[bj][n] = v[bj][n] * r2 * gv[bj][n]; }
;                 bf16_t* rowp = Z + (size_t)row * ldz + u.pn * BM + 64 * wc + 8 * fq;
; #pragma unroll
;                 for (int bj = 0; bj < 2; ++bj) { u32x4 w; w.x = cvtpk(v[bj][0][0], v[bj][0][1]); w.y = cvtpk(v[bj][0][2], v[bj][0][3]); w.z = cvtpk(v[bj][1][0], v[bj][1][1]); w.w = cvtpk(v[bj][1][2], v[bj][1][3]);
;                     *(u32x4*)(rowp + 32 * bj) = w; }
.LBB0_152:
	s_lshl_b32 s4, 1, s39
	s_and_b32 s19, s4, 0x2cf
	v_readlane_b32 s86, v254, 0
	v_readlane_b32 s87, v254, 1
	s_bfe_u32 s90, s81, 0x20006
	s_movk_i32 s91, 0x1400
	s_nop 1
	s_load_dwordx2 s[88:89], s[86:87], 0xe0
	v_mbcnt_lo_u32_b32 v176, -1, 0
	v_mbcnt_hi_u32_b32 v176, -1, v176
	v_bfe_u32 v174, v176, 4, 2
	v_lshlrev_b32_e32 v174, 4, v174
	v_lshl_add_u32 v168, s40, 8, v170
	v_lshl_add_u32 v169, v168, 6, v174
	v_add_u32_e32 v178, 0x2000, v169
	v_mad_u32_u24 v179, v168, s91, v174
	s_lshl_b32 s98, s39, 8
	s_mov_b32 s99, 0
	s_lshl_b32 s92, s39, 9
	s_lshl_b32 s4, s90, 7
	s_add_i32 s92, s92, s4
	s_add_u32 s100, s14, s92
	s_addc_u32 s101, s15, 0
	s_waitcnt lgkmcnt(0)
	s_add_u32 s70, s88, 0x3600000
	s_addc_u32 s71, s89, 0
	global_load_dwordx4 v[186:189], v169, s[70:71]
	global_load_dwordx4 v[190:193], v169, s[70:71] offset:1024
	global_load_dwordx4 v[194:197], v169, s[70:71] offset:2048
	global_load_dwordx4 v[198:201], v169, s[70:71] offset:3072
	global_load_dwordx4 v[202:205], v178, s[70:71]
	global_load_dwordx4 v[206:209], v178, s[70:71] offset:1024
	global_load_dwordx4 v[210:213], v178, s[70:71] offset:2048
	global_load_dwordx4 v[214:217], v178, s[70:71] offset:3072
	s_cmp_eq_u32 s19, 0
	s_cbranch_scc1 EZ2_plain
	v_lshl_add_u64 v[180:181], s[98:99], 0, v[160:161]
	global_load_dwordx4 v[64:67], v[180:181], off
	global_load_dwordx4 v[68:71], v[180:181], off offset:16
	global_load_dwordx4 v[72:75], v[180:181], off offset:128
	global_load_dwordx4 v[76:79], v[180:181], off offset:144
	s_waitcnt vmcnt(0)
	v_add_f32_e32 v186, v186, v187
	v_add_f32_e32 v188, v188, v189
	v_add_f32_e32 v186, v186, v188
	v_mov_b32_e32 v187, v186
	s_nop 1
	v_permlane16_swap_b32_e32 v186, v187
	v_add_f32_e32 v186, v186, v187
	v_mov_b32_e32 v187, v186
	s_nop 1
	v_permlane32_swap_b32_e32 v186, v187
	v_add_f32_e32 v186, v186, v187
	v_fma_f32 v186, v186, s82, v173
	v_rsq_f32_e32 v218, v186
	v_pk_mul_f32 v[224:225], v[128:129], v[128:129]
	v_pk_fma_f32 v[224:225], v[130:131], v[130:131], v[224:225]
	v_pk_fma_f32 v[224:225], v[132:133], v[132:133], v[224:225]
	v_pk_fma_f32 v[224:225], v[134:135], v[134:135], v[224:225]
	v_pk_fma_f32 v[224:225], v[136:137], v[136:137], v[224:225]
	v_pk_fma_f32 v[224:225], v[138:139], v[138:139], v[224:225]
	v_pk_fma_f32 v[224:225], v[140:141], v[140:141], v[224:225]
	v_pk_fma_f32 v[224:225], v[142:143], v[142:143], v[224:225]
	v_add_f32_e32 v220, v224, v225
	v_mul_f32_e32 v220, v220, v218
	v_mul_f32_e32 v220, v220, v218
	v_mov_b32_e32 v222, v220
	s_nop 1
	v_permlane16_swap_b32_e32 v220, v222
	v_add_f32_e32 v220, v220, v222
	v_mov_b32_e32 v222, v220
	s_nop 1
	v_permlane32_swap_b32_e32 v220, v222
	v_add_f32_e32 v220, v220, v222
	v_fmamk_f32 v220, v220, 0x3c800000, v173
	v_rsq_f32_e32 v220, v220
	s_nop 0
	v_mul_f32_e32 v218, v218, v220
	v_pk_mul_f32 v[226:227], v[64:65], v[218:219] op_sel_hi:[1,0]
	v_pk_mul_f32 v[140:141], v[140:141], v[226:227]
	v_pk_mul_f32 v[226:227], v[66:67], v[218:219] op_sel_hi:[1,0]
	v_pk_mul_f32 v[142:143], v[142:143], v[226:227]
	v_pk_mul_f32 v[226:227], v[68:69], v[218:219] op_sel_hi:[1,0]
	v_pk_mul_f32 v[136:137], v[136:137], v[226:227]
	v_pk_mul_f32 v[226:227], v[70:71], v[218:219] op_sel_hi:[1,0]
	v_pk_mul_f32 v[138:139], v[138:139], v[226:227]
	v_pk_mul_f32 v[226:227], v[72:73], v[218:219] op_sel_hi:[1,0]
	v_pk_mul_f32 v[132:133], v[132:133], v[226:227]
	v_pk_mul_f32 v[226:227], v[74:75], v[218:219] op_sel_hi:[1,0]
	v_pk_mul_f32 v[134:135], v[134:135], v[226:227]
	v_pk_mul_f32 v[226:227], v[76:77], v[218:219] op_sel_hi:[1,0]
	v_pk_mul_f32 v[128:129], v[128:129], v[226:227]
	v_pk_mul_f32 v[226:227], v[78:79], v[218:219] op_sel_hi:[1,0]
	v_pk_mul_f32 v[130:131], v[130:131], v[226:227]
	v_cvt_pk_bf16_f32 v242, v140, v141
	v_cvt_pk_bf16_f32 v243, v142, v143
	v_cvt_pk_bf16_f32 v244, v136, v137
	v_cvt_pk_bf16_f32 v245, v138, v139
	v_cvt_pk_bf16_f32 v246, v132, v133
	v_cvt_pk_bf16_f32 v247, v134, v135
	v_cvt_pk_bf16_f32 v248, v128, v129
	v_cvt_pk_bf16_f32 v249, v130, v131
	global_store_dwordx4 v179, v[242:245], s[100:101]
	global_store_dwordx4 v179, v[246:249], s[100:101] offset:64
	v_add_f32_e32 v190, v190, v191
	v_add_f32_e32 v192, v192, v193
	v_add_f32_e32 v190, v190, v192
	v_mov_b32_e32 v191, v190
	s_nop 1
	v_permlane16_swap_b32_e32 v190, v191
	v_add_f32_e32 v190, v190, v191
	v_mov_b32_e32 v191, v190
	s_nop 1
	v_permlane32_swap_b32_e32 v190, v191
	v_add_f32_e32 v190, v190, v191
	v_fma_f32 v190, v190, s82, v173
	v_rsq_f32_e32 v218, v190
	v_pk_mul_f32 v[224:225], v[112:113], v[112:113]
	v_pk_fma_f32 v[224:225], v[114:115], v[114:115], v[224:225]
	v_pk_fma_f32 v[224:225], v[116:117], v[116:117], v[224:225]
	v_pk_fma_f32 v[224:225], v[118:119], v[118:119], v[224:225]
	v_pk_fma_f32 v[224:225], v[120:121], v[120:121], v[224:225]
	v_pk_fma_f32 v[224:225], v[122:123], v[122:123], v[224:225]
	v_pk_fma_f32 v[224:225], v[124:125], v[124:125], v[224:225]
	v_pk_fma_f32 v[224:225], v[126:127], v[126:127], v[224:225]
	v_add_f32_e32 v220, v224, v225
	v_mul_f32_e32 v220, v220, v218
	v_mul_f32_e32 v220, v220, v218
	v_mov_b32_e32 v222, v220
	s_nop 1
	v_permlane16_swap_b32_e32 v220, v222
	v_add_f32_e32 v220, v220, v222
	v_mov_b32_e32 v222, v220
	s_nop 1
	v_permlane32_swap_b32_e32 v220, v222
	v_add_f32_e32 v220, v220, v222
	v_fmamk_f32 v220, v220, 0x3c800000, v173
	v_rsq_f32_e32 v220, v220
	s_nop 0
	v_mul_f32_e32 v218, v218, v220
	v_pk_mul_f32 v[226:227], v[64:65], v[218:219] op_sel_hi:[1,0]
	v_pk_mul_f32 v[124:125], v[124:125], v[226:227]
	v_pk_mul_f32 v[226:227], v[66:67], v[218:219] op_sel_hi:[1,0]
	v_pk_mul_f32 v[126:127], v[126:127], v[226:227]
	v_pk_mul_f32 v[226:227], v[68:69], v[218:219] op_sel_hi:[1,0]
; __device__ __forceinline__ unsigned cvtpk(float lo, float hi) { f32x2 v = {lo, hi}; bf16x2_t b = __builtin_convertvector(v, bf16x2_t); return __builtin_bit_cast(unsigned, b); }
;     __device__ __forceinline__ void operator()(const f32x4 (&acc)[2][2][4][2], const Unit& u, int wr, int wc, int fr, int fq) const {
;     ...
;                 const int row = u.pm * BM + ai * HALF + wr * 64 + m * 16 + fr;
;                 float rs = 1.f;
;                 if (PS) { const f32x4 p = *(const f32x4*)(PS + (size_t)row * 16 + 4 * fq); float s = (p[0] + p[1]) + (p[2] + p[3]); s = bfly_add<16>(s); s = bfly_add<32>(s); rs = rsqrtf(s * (1.f / DM) + EPS); }
;                 f32x4 v[2][2]; float ss = 0.f;
; #pragma unroll
;                 for (int bj = 0; bj < 2; ++bj)
; #pragma unroll
;                     for (int n = 0; n < 2; ++n) { v[bj][n] = acc[ai][bj][m][n] * rs; const f32x4 x = v[bj][n]; ss += (x[0] * x[0] + x[1] * x[1]) + (x[2] * x[2] + x[3] * x[3]); }
;                 if (nrm) { ss = bfly_add<16>(ss); ss = bfly_add<32>(ss); const float r2 = rsqrtf(ss * (1.f / 64.f) + EPS);
; #pragma unroll
;                     for (int bj = 0; bj < 2; ++bj)
; #pragma unroll
;                         for (int n = 0; n < 2; ++n) v[bj][n] = v[bj][n] * r2 * gv[bj][n]; }
;                 bf16_t* rowp = Z + (size_t)row * ldz + u.pn * BM + 64 * wc + 8 * fq;
; #pragma unroll
;                 for (int bj = 0; bj < 2; ++bj) { u32x4 w; w.x = cvtpk(v[bj][0][0], v[bj][0][1]); w.y = cvtpk(v[bj][0][2], v[bj][0][3]); w.z = cvtpk(v[bj][1][0], v[bj][1][1]); w.w = cvtpk(v[bj][1][2], v[bj][1][3]);
;                     *(u32x4*)(rowp + 32 * bj) = w; }
	v_pk_mul_f32 v[120:121], v[120:121], v[226:227]
	v_pk_mul_f32 v[226:227], v[70:71], v[218:219] op_sel_hi:[1,0]
	v_pk_mul_f32 v[122:123], v[122:123], v[226:227]
	v_pk_mul_f32 v[226:227], v[72:73], v[218:219] op_sel_hi:[1,0]
	v_pk_mul_f32 v[116:117], v[116:117], v[226:227]
	v_pk_mul_f32 v[226:227], v[74:75], v[218:219] op_sel_hi:[1,0]
	v_pk_mul_f32 v[118:119], v[118:119], v[226:227]
	v_pk_mul_f32 v[226:227], v[76:77], v[218:219] op_sel_hi:[1,0]
	v_pk_mul_f32 v[112:113], v[112:113], v[226:227]
	v_pk_mul_f32 v[226:227], v[78:79], v[218:219] op_sel_hi:[1,0]
	v_pk_mul_f32 v[114:115], v[114:115], v[226:227]
	v_cvt_pk_bf16_f32 v242, v124, v125
	v_cvt_pk_bf16_f32 v243, v126, v127
	v_cvt_pk_bf16_f32 v244, v120, v121
	v_cvt_pk_bf16_f32 v245, v122, v123
	v_cvt_pk_bf16_f32 v246, v116, v117
	v_cvt_pk_bf16_f32 v247, v118, v119
	v_cvt_pk_bf16_f32 v248, v112, v113
	v_cvt_pk_bf16_f32 v249, v114, v115
	v_add_u32_e32 v250, 0x14000, v179
	global_store_dwordx4 v250, v[242:245], s[100:101]
	global_store_dwordx4 v250, v[246:249], s[100:101] offset:64
	v_add_f32_e32 v194, v194, v195
	v_add_f32_e32 v196, v196, v197
	v_add_f32_e32 v194, v194, v196
	v_mov_b32_e32 v195, v194
	s_nop 1
	v_permlane16_swap_b32_e32 v194, v195
	v_add_f32_e32 v194, v194, v195
	v_mov_b32_e32 v195, v194
	s_nop 1
	v_permlane32_swap_b32_e32 v194, v195
	v_add_f32_e32 v194, v194, v195
	v_fma_f32 v194, v194, s82, v173
	v_rsq_f32_e32 v218, v194
	v_pk_mul_f32 v[224:225], v[96:97], v[96:97]
	v_pk_fma_f32 v[224:225], v[98:99], v[98:99], v[224:225]
	v_pk_fma_f32 v[224:225], v[100:101], v[100:101], v[224:225]
	v_pk_fma_f32 v[224:225], v[102:103], v[102:103], v[224:225]
	v_pk_fma_f32 v[224:225], v[104:105], v[104:105], v[224:225]
	v_pk_fma_f32 v[224:225], v[106:107], v[106:107], v[224:225]
	v_pk_fma_f32 v[224:225], v[108:109], v[108:109], v[224:225]
	v_pk_fma_f32 v[224:225], v[110:111], v[110:111], v[224:225]
	v_add_f32_e32 v220, v224, v225
	v_mul_f32_e32 v220, v220, v218
	v_mul_f32_e32 v220, v220, v218
	v_mov_b32_e32 v222, v220
	s_nop 1
	v_permlane16_swap_b32_e32 v220, v222
	v_add_f32_e32 v220, v220, v222
	v_mov_b32_e32 v222, v220
	s_nop 1
	v_permlane32_swap_b32_e32 v220, v222
	v_add_f32_e32 v220, v220, v222
	v_fmamk_f32 v220, v220, 0x3c800000, v173
	v_rsq_f32_e32 v220, v220
	s_nop 0
	v_mul_f32_e32 v218, v218, v220
	v_pk_mul_f32 v[226:227], v[64:65], v[218:219] op_sel_hi:[1,0]
	v_pk_mul_f32 v[108:109], v[108:109], v[226:227]
	v_pk_mul_f32 v[226:227], v[66:67], v[218:219] op_sel_hi:[1,0]
	v_pk_mul_f32 v[110:111], v[110:111], v[226:227]
	v_pk_mul_f32 v[226:227], v[68:69], v[218:219] op_sel_hi:[1,0]
	v_pk_mul_f32 v[104:105], v[104:105], v[226:227]
	v_pk_mul_f32 v[226:227], v[70:71], v[218:219] op_sel_hi:[1,0]
	v_pk_mul_f32 v[106:107], v[106:107], v[226:227]
	v_pk_mul_f32 v[226:227], v[72:73], v[218:219] op_sel_hi:[1,0]
	v_pk_mul_f32 v[100:101], v[100:101], v[226:227]
	v_pk_mul_f32 v[226:227], v[74:75], v[218:219] op_sel_hi:[1,0]
	v_pk_mul_f32 v[102:103], v[102:103], v[226:227]
	v_pk_mul_f32 v[226:227], v[76:77], v[218:219] op_sel_hi:[1,0]
	v_pk_mul_f32 v[96:97], v[96:97], v[226:227]
	v_pk_mul_f32 v[226:227], v[78:79], v[218:219] op_sel_hi:[1,0]
	v_pk_mul_f32 v[98:99], v[98:99], v[226:227]
	v_cvt_pk_bf16_f32 v242, v108, v109
	v_cvt_pk_bf16_f32 v243, v110, v111
	v_cvt_pk_bf16_f32 v244, v104, v105
	v_cvt_pk_bf16_f32 v245, v106, v107
	v_cvt_pk_bf16_f32 v246, v100, v101
	v_cvt_pk_bf16_f32 v247, v102, v103
	v_cvt_pk_bf16_f32 v248, v96, v97
	v_cvt_pk_bf16_f32 v249, v98, v99
	v_add_u32_e32 v250, 0x28000, v179
	global_store_dwordx4 v250, v[242:245], s[100:101]
	global_store_dwordx4 v250, v[246:249], s[100:101] offset:64
	v_add_f32_e32 v198, v198, v199
	v_add_f32_e32 v200, v200, v201
	v_add_f32_e32 v198, v198, v200
	v_mov_b32_e32 v199, v198
	s_nop 1
	v_permlane16_swap_b32_e32 v198, v199
	v_add_f32_e32 v198, v198, v199
	v_mov_b32_e32 v199, v198
	s_nop 1
	v_permlane32_swap_b32_e32 v198, v199
	v_add_f32_e32 v198, v198, v199
	v_fma_f32 v198, v198, s82, v173
	v_rsq_f32_e32 v218, v198
	v_pk_mul_f32 v[224:225], v[80:81], v[80:81]
	v_pk_fma_f32 v[224:225], v[82:83], v[82:83], v[224:225]
	v_pk_fma_f32 v[224:225], v[84:85], v[84:85], v[224:225]
	v_pk_fma_f32 v[224:225], v[86:87], v[86:87], v[224:225]
	v_pk_fma_f32 v[224:225], v[88:89], v[88:89], v[224:225]
	v_pk_fma_f32 v[224:225], v[90:91], v[90:91], v[224:225]
	v_pk_fma_f32 v[224:225], v[92:93], v[92:93], v[224:225]
	v_pk_fma_f32 v[224:225], v[94:95], v[94:95], v[224:225]
	v_add_f32_e32 v220, v224, v225
	v_mul_f32_e32 v220, v220, v218
	v_mul_f32_e32 v220, v220, v218
	v_mov_b32_e32 v222, v220
	s_nop 1
	v_permlane16_swap_b32_e32 v220, v222
	v_add_f32_e32 v220, v220, v222
	v_mov_b32_e32 v222, v220
	s_nop 1
	v_permlane32_swap_b32_e32 v220, v222
	v_add_f32_e32 v220, v220, v222
	v_fmamk_f32 v220, v220, 0x3c800000, v173
	v_rsq_f32_e32 v220, v220
	s_nop 0
	v_mul_f32_e32 v218, v218, v220
	v_pk_mul_f32 v[226:227], v[64:65], v[218:219] op_sel_hi:[1,0]
	v_pk_mul_f32 v[92:93], v[92:93], v[226:227]
	v_pk_mul_f32 v[226:227], v[66:67], v[218:219] op_sel_hi:[1,0]
	v_pk_mul_f32 v[94:95], v[94:95], v[226:227]
	v_pk_mul_f32 v[226:227], v[68:69], v[218:219] op_sel_hi:[1,0]
	v_pk_mul_f32 v[88:89], v[88:89], v[226:227]
	v_pk_mul_f32 v[226:227], v[70:71], v[218:219] op_sel_hi:[1,0]
	v_pk_mul_f32 v[90:91], v[90:91], v[226:227]
	v_pk_mul_f32 v[226:227], v[72:73], v[218:219] op_sel_hi:[1,0]
	v_pk_mul_f32 v[84:85], v[84:85], v[226:227]
	v_pk_mul_f32 v[226:227], v[74:75], v[218:219] op_sel_hi:[1,0]
	v_pk_mul_f32 v[86:87], v[86:87], v[226:227]
	v_pk_mul_f32 v[226:227], v[76:77], v[218:219] op_sel_hi:[1,0]
	v_pk_mul_f32 v[80:81], v[80:81], v[226:227]
	v_pk_mul_f32 v[226:227], v[78:79], v[218:219] op_sel_hi:[1,0]
; __device__ __forceinline__ unsigned cvtpk(float lo, float hi) { f32x2 v = {lo, hi}; bf16x2_t b = __builtin_convertvector(v, bf16x2_t); return __builtin_bit_cast(unsigned, b); }
;     __device__ __forceinline__ void operator()(const f32x4 (&acc)[2][2][4][2], const Unit& u, int wr, int wc, int fr, int fq) const {
;     ...
;                 const int row = u.pm * BM + ai * HALF + wr * 64 + m * 16 + fr;
;                 float rs = 1.f;
;                 if (PS) { const f32x4 p = *(const f32x4*)(PS + (size_t)row * 16 + 4 * fq); float s = (p[0] + p[1]) + (p[2] + p[3]); s = bfly_add<16>(s); s = bfly_add<32>(s); rs = rsqrtf(s * (1.f / DM) + EPS); }
;                 f32x4 v[2][2]; float ss = 0.f;
; #pragma unroll
;                 for (int bj = 0; bj < 2; ++bj)
; #pragma unroll
;                     for (int n = 0; n < 2; ++n) { v[bj][n] = acc[ai][bj][m][n] * rs; const f32x4 x = v[bj][n]; ss += (x[0] * x[0] + x[1] * x[1]) + (x[2] * x[2] + x[3] * x[3]); }
;                 if (nrm) { ss = bfly_add<16>(ss); ss = bfly_add<32>(ss); const float r2 = rsqrtf(ss * (1.f / 64.f) + EPS);
; #pragma unroll
;                     for (int bj = 0; bj < 2; ++bj)
; #pragma unroll
;                         for (int n = 0; n < 2; ++n) v[bj][n] = v[bj][n] * r2 * gv[bj][n]; }
;                 bf16_t* rowp = Z + (size_t)row * ldz + u.pn * BM + 64 * wc + 8 * fq;
; #pragma unroll
;                 for (int bj = 0; bj < 2; ++bj) { u32x4 w; w.x = cvtpk(v[bj][0][0], v[bj][0][1]); w.y = cvtpk(v[bj][0][2], v[bj][0][3]); w.z = cvtpk(v[bj][1][0], v[bj][1][1]); w.w = cvtpk(v[bj][1][2], v[bj][1][3]);
;                     *(u32x4*)(rowp + 32 * bj) = w; }
	v_pk_mul_f32 v[82:83], v[82:83], v[226:227]
	v_cvt_pk_bf16_f32 v242, v92, v93
	v_cvt_pk_bf16_f32 v243, v94, v95
	v_cvt_pk_bf16_f32 v244, v88, v89
	v_cvt_pk_bf16_f32 v245, v90, v91
	v_cvt_pk_bf16_f32 v246, v84, v85
	v_cvt_pk_bf16_f32 v247, v86, v87
	v_cvt_pk_bf16_f32 v248, v80, v81
	v_cvt_pk_bf16_f32 v249, v82, v83
	v_add_u32_e32 v250, 0x3c000, v179
	global_store_dwordx4 v250, v[242:245], s[100:101]
	global_store_dwordx4 v250, v[246:249], s[100:101] offset:64
	v_add_f32_e32 v202, v202, v203
	v_add_f32_e32 v204, v204, v205
	v_add_f32_e32 v202, v202, v204
	v_mov_b32_e32 v203, v202
	s_nop 1
	v_permlane16_swap_b32_e32 v202, v203
	v_add_f32_e32 v202, v202, v203
	v_mov_b32_e32 v203, v202
	s_nop 1
	v_permlane32_swap_b32_e32 v202, v203
	v_add_f32_e32 v202, v202, v203
	v_fma_f32 v202, v202, s82, v173
	v_rsq_f32_e32 v218, v202
	v_pk_mul_f32 v[224:225], v[48:49], v[48:49]
	v_pk_fma_f32 v[224:225], v[50:51], v[50:51], v[224:225]
	v_pk_fma_f32 v[224:225], v[52:53], v[52:53], v[224:225]
	v_pk_fma_f32 v[224:225], v[54:55], v[54:55], v[224:225]
	v_pk_fma_f32 v[224:225], v[56:57], v[56:57], v[224:225]
	v_pk_fma_f32 v[224:225], v[58:59], v[58:59], v[224:225]
	v_pk_fma_f32 v[224:225], v[60:61], v[60:61], v[224:225]
	v_pk_fma_f32 v[224:225], v[62:63], v[62:63], v[224:225]
	v_add_f32_e32 v220, v224, v225
	v_mul_f32_e32 v220, v220, v218
	v_mul_f32_e32 v220, v220, v218
	v_mov_b32_e32 v222, v220
	s_nop 1
	v_permlane16_swap_b32_e32 v220, v222
	v_add_f32_e32 v220, v220, v222
	v_mov_b32_e32 v222, v220
	s_nop 1
	v_permlane32_swap_b32_e32 v220, v222
	v_add_f32_e32 v220, v220, v222
	v_fmamk_f32 v220, v220, 0x3c800000, v173
	v_rsq_f32_e32 v220, v220
	s_nop 0
	v_mul_f32_e32 v218, v218, v220
	v_pk_mul_f32 v[226:227], v[64:65], v[218:219] op_sel_hi:[1,0]
	v_pk_mul_f32 v[60:61], v[60:61], v[226:227]
	v_pk_mul_f32 v[226:227], v[66:67], v[218:219] op_sel_hi:[1,0]
	v_pk_mul_f32 v[62:63], v[62:63], v[226:227]
	v_pk_mul_f32 v[226:227], v[68:69], v[218:219] op_sel_hi:[1,0]
	v_pk_mul_f32 v[56:57], v[56:57], v[226:227]
	v_pk_mul_f32 v[226:227], v[70:71], v[218:219] op_sel_hi:[1,0]
	v_pk_mul_f32 v[58:59], v[58:59], v[226:227]
	v_pk_mul_f32 v[226:227], v[72:73], v[218:219] op_sel_hi:[1,0]
	v_pk_mul_f32 v[52:53], v[52:53], v[226:227]
	v_pk_mul_f32 v[226:227], v[74:75], v[218:219] op_sel_hi:[1,0]
	v_pk_mul_f32 v[54:55], v[54:55], v[226:227]
	v_pk_mul_f32 v[226:227], v[76:77], v[218:219] op_sel_hi:[1,0]
	v_pk_mul_f32 v[48:49], v[48:49], v[226:227]
	v_pk_mul_f32 v[226:227], v[78:79], v[218:219] op_sel_hi:[1,0]
	v_pk_mul_f32 v[50:51], v[50:51], v[226:227]
	v_cvt_pk_bf16_f32 v242, v60, v61
	v_cvt_pk_bf16_f32 v243, v62, v63
	v_cvt_pk_bf16_f32 v244, v56, v57
	v_cvt_pk_bf16_f32 v245, v58, v59
	v_cvt_pk_bf16_f32 v246, v52, v53
	v_cvt_pk_bf16_f32 v247, v54, v55
	v_cvt_pk_bf16_f32 v248, v48, v49
	v_cvt_pk_bf16_f32 v249, v50, v51
	v_add_u32_e32 v250, 0xa0000, v179
	global_store_dwordx4 v250, v[242:245], s[100:101]
	global_store_dwordx4 v250, v[246:249], s[100:101] offset:64
	v_add_f32_e32 v206, v206, v207
	v_add_f32_e32 v208, v208, v209
	v_add_f32_e32 v206, v206, v208
	v_mov_b32_e32 v207, v206
	s_nop 1
	v_permlane16_swap_b32_e32 v206, v207
	v_add_f32_e32 v206, v206, v207
	v_mov_b32_e32 v207, v206
	s_nop 1
	v_permlane32_swap_b32_e32 v206, v207
	v_add_f32_e32 v206, v206, v207
	v_fma_f32 v206, v206, s82, v173
	v_rsq_f32_e32 v218, v206
	v_pk_mul_f32 v[224:225], v[32:33], v[32:33]
	v_pk_fma_f32 v[224:225], v[34:35], v[34:35], v[224:225]
	v_pk_fma_f32 v[224:225], v[36:37], v[36:37], v[224:225]
	v_pk_fma_f32 v[224:225], v[38:39], v[38:39], v[224:225]
	v_pk_fma_f32 v[224:225], v[40:41], v[40:41], v[224:225]
	v_pk_fma_f32 v[224:225], v[42:43], v[42:43], v[224:225]
	v_pk_fma_f32 v[224:225], v[44:45], v[44:45], v[224:225]
	v_pk_fma_f32 v[224:225], v[46:47], v[46:47], v[224:225]
	v_add_f32_e32 v220, v224, v225
	v_mul_f32_e32 v220, v220, v218
	v_mul_f32_e32 v220, v220, v218
	v_mov_b32_e32 v222, v220
	s_nop 1
	v_permlane16_swap_b32_e32 v220, v222
	v_add_f32_e32 v220, v220, v222
	v_mov_b32_e32 v222, v220
	s_nop 1
	v_permlane32_swap_b32_e32 v220, v222
	v_add_f32_e32 v220, v220, v222
	v_fmamk_f32 v220, v220, 0x3c800000, v173
	v_rsq_f32_e32 v220, v220
	s_nop 0
	v_mul_f32_e32 v218, v218, v220
	v_pk_mul_f32 v[226:227], v[64:65], v[218:219] op_sel_hi:[1,0]
	v_pk_mul_f32 v[44:45], v[44:45], v[226:227]
	v_pk_mul_f32 v[226:227], v[66:67], v[218:219] op_sel_hi:[1,0]
	v_pk_mul_f32 v[46:47], v[46:47], v[226:227]
	v_pk_mul_f32 v[226:227], v[68:69], v[218:219] op_sel_hi:[1,0]
	v_pk_mul_f32 v[40:41], v[40:41], v[226:227]
	v_pk_mul_f32 v[226:227], v[70:71], v[218:219] op_sel_hi:[1,0]
	v_pk_mul_f32 v[42:43], v[42:43], v[226:227]
	v_pk_mul_f32 v[226:227], v[72:73], v[218:219] op_sel_hi:[1,0]
	v_pk_mul_f32 v[36:37], v[36:37], v[226:227]
	v_pk_mul_f32 v[226:227], v[74:75], v[218:219] op_sel_hi:[1,0]
	v_pk_mul_f32 v[38:39], v[38:39], v[226:227]
	v_pk_mul_f32 v[226:227], v[76:77], v[218:219] op_sel_hi:[1,0]
	v_pk_mul_f32 v[32:33], v[32:33], v[226:227]
	v_pk_mul_f32 v[226:227], v[78:79], v[218:219] op_sel_hi:[1,0]
	v_pk_mul_f32 v[34:35], v[34:35], v[226:227]
	v_cvt_pk_bf16_f32 v242, v44, v45
	v_cvt_pk_bf16_f32 v243, v46, v47
	v_cvt_pk_bf16_f32 v244, v40, v41
	v_cvt_pk_bf16_f32 v245, v42, v43
	v_cvt_pk_bf16_f32 v246, v36, v37
	v_cvt_pk_bf16_f32 v247, v38, v39
	v_cvt_pk_bf16_f32 v248, v32, v33
	v_cvt_pk_bf16_f32 v249, v34, v35
	v_add_u32_e32 v250, 0xb4000, v179
	global_store_dwordx4 v250, v[242:245], s[100:101]
	global_store_dwordx4 v250, v[246:249], s[100:101] offset:64
	v_add_f32_e32 v210, v210, v211
	v_add_f32_e32 v212, v212, v213
	v_add_f32_e32 v210, v210, v212
	v_mov_b32_e32 v211, v210
	s_nop 1
	v_permlane16_swap_b32_e32 v210, v211
; __device__ __forceinline__ unsigned cvtpk(float lo, float hi) { f32x2 v = {lo, hi}; bf16x2_t b = __builtin_convertvector(v, bf16x2_t); return __builtin_bit_cast(unsigned, b); }
;     __device__ __forceinline__ void operator()(const f32x4 (&acc)[2][2][4][2], const Unit& u, int wr, int wc, int fr, int fq) const {
;     ...
;                 const int row = u.pm * BM + ai * HALF + wr * 64 + m * 16 + fr;
;                 float rs = 1.f;
;                 if (PS) { const f32x4 p = *(const f32x4*)(PS + (size_t)row * 16 + 4 * fq); float s = (p[0] + p[1]) + (p[2] + p[3]); s = bfly_add<16>(s); s = bfly_add<32>(s); rs = rsqrtf(s * (1.f / DM) + EPS); }
;                 f32x4 v[2][2]; float ss = 0.f;
; #pragma unroll
;                 for (int bj = 0; bj < 2; ++bj)
; #pragma unroll
;                     for (int n = 0; n < 2; ++n) { v[bj][n] = acc[ai][bj][m][n] * rs; const f32x4 x = v[bj][n]; ss += (x[0] * x[0] + x[1] * x[1]) + (x[2] * x[2] + x[3] * x[3]); }
;                 if (nrm) { ss = bfly_add<16>(ss); ss = bfly_add<32>(ss); const float r2 = rsqrtf(ss * (1.f / 64.f) + EPS);
; #pragma unroll
;                     for (int bj = 0; bj < 2; ++bj)
; #pragma unroll
;                         for (int n = 0; n < 2; ++n) v[bj][n] = v[bj][n] * r2 * gv[bj][n]; }
;                 bf16_t* rowp = Z + (size_t)row * ldz + u.pn * BM + 64 * wc + 8 * fq;
; #pragma unroll
;                 for (int bj = 0; bj < 2; ++bj) { u32x4 w; w.x = cvtpk(v[bj][0][0], v[bj][0][1]); w.y = cvtpk(v[bj][0][2], v[bj][0][3]); w.z = cvtpk(v[bj][1][0], v[bj][1][1]); w.w = cvtpk(v[bj][1][2], v[bj][1][3]);
;                     *(u32x4*)(rowp + 32 * bj) = w; }
	v_add_f32_e32 v210, v210, v211
	v_mov_b32_e32 v211, v210
	s_nop 1
	v_permlane32_swap_b32_e32 v210, v211
	v_add_f32_e32 v210, v210, v211
	v_fma_f32 v210, v210, s82, v173
	v_rsq_f32_e32 v218, v210
	v_pk_mul_f32 v[224:225], v[16:17], v[16:17]
	v_pk_fma_f32 v[224:225], v[18:19], v[18:19], v[224:225]
	v_pk_fma_f32 v[224:225], v[20:21], v[20:21], v[224:225]
	v_pk_fma_f32 v[224:225], v[22:23], v[22:23], v[224:225]
	v_pk_fma_f32 v[224:225], v[24:25], v[24:25], v[224:225]
	v_pk_fma_f32 v[224:225], v[26:27], v[26:27], v[224:225]
	v_pk_fma_f32 v[224:225], v[28:29], v[28:29], v[224:225]
	v_pk_fma_f32 v[224:225], v[30:31], v[30:31], v[224:225]
	v_add_f32_e32 v220, v224, v225
	v_mul_f32_e32 v220, v220, v218
	v_mul_f32_e32 v220, v220, v218
	v_mov_b32_e32 v222, v220
	s_nop 1
	v_permlane16_swap_b32_e32 v220, v222
	v_add_f32_e32 v220, v220, v222
	v_mov_b32_e32 v222, v220
	s_nop 1
	v_permlane32_swap_b32_e32 v220, v222
	v_add_f32_e32 v220, v220, v222
	v_fmamk_f32 v220, v220, 0x3c800000, v173
	v_rsq_f32_e32 v220, v220
	s_nop 0
	v_mul_f32_e32 v218, v218, v220
	v_pk_mul_f32 v[226:227], v[64:65], v[218:219] op_sel_hi:[1,0]
	v_pk_mul_f32 v[28:29], v[28:29], v[226:227]
	v_pk_mul_f32 v[226:227], v[66:67], v[218:219] op_sel_hi:[1,0]
	v_pk_mul_f32 v[30:31], v[30:31], v[226:227]
	v_pk_mul_f32 v[226:227], v[68:69], v[218:219] op_sel_hi:[1,0]
	v_pk_mul_f32 v[24:25], v[24:25], v[226:227]
	v_pk_mul_f32 v[226:227], v[70:71], v[218:219] op_sel_hi:[1,0]
	v_pk_mul_f32 v[26:27], v[26:27], v[226:227]
	v_pk_mul_f32 v[226:227], v[72:73], v[218:219] op_sel_hi:[1,0]
	v_pk_mul_f32 v[20:21], v[20:21], v[226:227]
	v_pk_mul_f32 v[226:227], v[74:75], v[218:219] op_sel_hi:[1,0]
	v_pk_mul_f32 v[22:23], v[22:23], v[226:227]
	v_pk_mul_f32 v[226:227], v[76:77], v[218:219] op_sel_hi:[1,0]
	v_pk_mul_f32 v[16:17], v[16:17], v[226:227]
	v_pk_mul_f32 v[226:227], v[78:79], v[218:219] op_sel_hi:[1,0]
	v_pk_mul_f32 v[18:19], v[18:19], v[226:227]
	v_cvt_pk_bf16_f32 v242, v28, v29
	v_cvt_pk_bf16_f32 v243, v30, v31
	v_cvt_pk_bf16_f32 v244, v24, v25
	v_cvt_pk_bf16_f32 v245, v26, v27
	v_cvt_pk_bf16_f32 v246, v20, v21
	v_cvt_pk_bf16_f32 v247, v22, v23
	v_cvt_pk_bf16_f32 v248, v16, v17
	v_cvt_pk_bf16_f32 v249, v18, v19
	v_add_u32_e32 v250, 0xc8000, v179
	global_store_dwordx4 v250, v[242:245], s[100:101]
	global_store_dwordx4 v250, v[246:249], s[100:101] offset:64
	v_add_f32_e32 v214, v214, v215
	v_add_f32_e32 v216, v216, v217
	v_add_f32_e32 v214, v214, v216
	v_mov_b32_e32 v215, v214
	s_nop 1
	v_permlane16_swap_b32_e32 v214, v215
	v_add_f32_e32 v214, v214, v215
	v_mov_b32_e32 v215, v214
	s_nop 1
	v_permlane32_swap_b32_e32 v214, v215
	v_add_f32_e32 v214, v214, v215
	v_fma_f32 v214, v214, s82, v173
	v_rsq_f32_e32 v218, v214
	v_pk_mul_f32 v[224:225], v[0:1], v[0:1]
	v_pk_fma_f32 v[224:225], v[2:3], v[2:3], v[224:225]
	v_pk_fma_f32 v[224:225], v[4:5], v[4:5], v[224:225]
	v_pk_fma_f32 v[224:225], v[6:7], v[6:7], v[224:225]
	v_pk_fma_f32 v[224:225], v[8:9], v[8:9], v[224:225]
	v_pk_fma_f32 v[224:225], v[10:11], v[10:11], v[224:225]
	v_pk_fma_f32 v[224:225], v[12:13], v[12:13], v[224:225]
	v_pk_fma_f32 v[224:225], v[14:15], v[14:15], v[224:225]
	v_add_f32_e32 v220, v224, v225
	v_mul_f32_e32 v220, v220, v218
	v_mul_f32_e32 v220, v220, v218
	v_mov_b32_e32 v222, v220
	s_nop 1
	v_permlane16_swap_b32_e32 v220, v222
	v_add_f32_e32 v220, v220, v222
	v_mov_b32_e32 v222, v220
	s_nop 1
	v_permlane32_swap_b32_e32 v220, v222
	v_add_f32_e32 v220, v220, v222
	v_fmamk_f32 v220, v220, 0x3c800000, v173
	v_rsq_f32_e32 v220, v220
	s_nop 0
	v_mul_f32_e32 v218, v218, v220
	v_pk_mul_f32 v[226:227], v[64:65], v[218:219] op_sel_hi:[1,0]
	v_pk_mul_f32 v[12:13], v[12:13], v[226:227]
	v_pk_mul_f32 v[226:227], v[66:67], v[218:219] op_sel_hi:[1,0]
	v_pk_mul_f32 v[14:15], v[14:15], v[226:227]
	v_pk_mul_f32 v[226:227], v[68:69], v[218:219] op_sel_hi:[1,0]
	v_pk_mul_f32 v[8:9], v[8:9], v[226:227]
	v_pk_mul_f32 v[226:227], v[70:71], v[218:219] op_sel_hi:[1,0]
	v_pk_mul_f32 v[10:11], v[10:11], v[226:227]
	v_pk_mul_f32 v[226:227], v[72:73], v[218:219] op_sel_hi:[1,0]
	v_pk_mul_f32 v[4:5], v[4:5], v[226:227]
	v_pk_mul_f32 v[226:227], v[74:75], v[218:219] op_sel_hi:[1,0]
	v_pk_mul_f32 v[6:7], v[6:7], v[226:227]
	v_pk_mul_f32 v[226:227], v[76:77], v[218:219] op_sel_hi:[1,0]
	v_pk_mul_f32 v[0:1], v[0:1], v[226:227]
	v_pk_mul_f32 v[226:227], v[78:79], v[218:219] op_sel_hi:[1,0]
	v_pk_mul_f32 v[2:3], v[2:3], v[226:227]
	v_cvt_pk_bf16_f32 v242, v12, v13
	v_cvt_pk_bf16_f32 v243, v14, v15
	v_cvt_pk_bf16_f32 v244, v8, v9
	v_cvt_pk_bf16_f32 v245, v10, v11
	v_cvt_pk_bf16_f32 v246, v4, v5
	v_cvt_pk_bf16_f32 v247, v6, v7
	v_cvt_pk_bf16_f32 v248, v0, v1
	v_cvt_pk_bf16_f32 v249, v2, v3
	v_add_u32_e32 v250, 0xdc000, v179
	global_store_dwordx4 v250, v[242:245], s[100:101]
	global_store_dwordx4 v250, v[246:249], s[100:101] offset:64
	s_branch EZ2_done
; __device__ __forceinline__ unsigned cvtpk(float lo, float hi) { f32x2 v = {lo, hi}; bf16x2_t b = __builtin_convertvector(v, bf16x2_t); return __builtin_bit_cast(unsigned, b); }
;     __device__ __forceinline__ void operator()(const f32x4 (&acc)[2][2][4][2], const Unit& u, int wr, int wc, int fr, int fq) const {
;     ...
;                 const int row = u.pm * BM + ai * HALF + wr * 64 + m * 16 + fr;
;                 float rs = 1.f;
;                 if (PS) { const f32x4 p = *(const f32x4*)(PS + (size_t)row * 16 + 4 * fq); float s = (p[0] + p[1]) + (p[2] + p[3]); s = bfly_add<16>(s); s = bfly_add<32>(s); rs = rsqrtf(s * (1.f / DM) + EPS); }
;                 f32x4 v[2][2]; float ss = 0.f;
; #pragma unroll
;                 for (int bj = 0; bj < 2; ++bj)
; #pragma unroll
;                     for (int n = 0; n < 2; ++n) { v[bj][n] = acc[ai][bj][m][n] * rs; const f32x4 x = v[bj][n]; ss += (x[0] * x[0] + x[1] * x[1]) + (x[2] * x[2] + x[3] * x[3]); }
;                 if (nrm) { ss = bfly_add<16>(ss); ss = bfly_add<32>(ss); const float r2 = rsqrtf(ss * (1.f / 64.f) + EPS);
; #pragma unroll
;                     for (int bj = 0; bj < 2; ++bj)
; #pragma unroll
;                         for (int n = 0; n < 2; ++n) v[bj][n] = v[bj][n] * r2 * gv[bj][n]; }
;                 bf16_t* rowp = Z + (size_t)row * ldz + u.pn * BM + 64 * wc + 8 * fq;
; #pragma unroll
;                 for (int bj = 0; bj < 2; ++bj) { u32x4 w; w.x = cvtpk(v[bj][0][0], v[bj][0][1]); w.y = cvtpk(v[bj][0][2], v[bj][0][3]); w.z = cvtpk(v[bj][1][0], v[bj][1][1]); w.w = cvtpk(v[bj][1][2], v[bj][1][3]);
;                     *(u32x4*)(rowp + 32 * bj) = w; }
EZ2_plain:
	s_waitcnt vmcnt(0)
	v_add_f32_e32 v186, v186, v187
	v_add_f32_e32 v188, v188, v189
	v_add_f32_e32 v186, v186, v188
	v_mov_b32_e32 v187, v186
	s_nop 1
	v_permlane16_swap_b32_e32 v186, v187
	v_add_f32_e32 v186, v186, v187
	v_mov_b32_e32 v187, v186
	s_nop 1
	v_permlane32_swap_b32_e32 v186, v187
	v_add_f32_e32 v186, v186, v187
	v_fma_f32 v186, v186, s82, v173
	v_rsq_f32_e32 v218, v186
	s_nop 0
	v_pk_mul_f32 v[128:129], v[128:129], v[218:219] op_sel_hi:[1,0]
	v_pk_mul_f32 v[130:131], v[130:131], v[218:219] op_sel_hi:[1,0]
	v_pk_mul_f32 v[132:133], v[132:133], v[218:219] op_sel_hi:[1,0]
	v_pk_mul_f32 v[134:135], v[134:135], v[218:219] op_sel_hi:[1,0]
	v_pk_mul_f32 v[136:137], v[136:137], v[218:219] op_sel_hi:[1,0]
	v_pk_mul_f32 v[138:139], v[138:139], v[218:219] op_sel_hi:[1,0]
	v_pk_mul_f32 v[140:141], v[140:141], v[218:219] op_sel_hi:[1,0]
	v_pk_mul_f32 v[142:143], v[142:143], v[218:219] op_sel_hi:[1,0]
	v_cvt_pk_bf16_f32 v242, v140, v141
	v_cvt_pk_bf16_f32 v243, v142, v143
	v_cvt_pk_bf16_f32 v244, v136, v137
	v_cvt_pk_bf16_f32 v245, v138, v139
	v_cvt_pk_bf16_f32 v246, v132, v133
	v_cvt_pk_bf16_f32 v247, v134, v135
	v_cvt_pk_bf16_f32 v248, v128, v129
	v_cvt_pk_bf16_f32 v249, v130, v131
	global_store_dwordx4 v179, v[242:245], s[100:101]
	global_store_dwordx4 v179, v[246:249], s[100:101] offset:64
	v_add_f32_e32 v190, v190, v191
	v_add_f32_e32 v192, v192, v193
	v_add_f32_e32 v190, v190, v192
	v_mov_b32_e32 v191, v190
	s_nop 1
	v_permlane16_swap_b32_e32 v190, v191
	v_add_f32_e32 v190, v190, v191
	v_mov_b32_e32 v191, v190
	s_nop 1
	v_permlane32_swap_b32_e32 v190, v191
	v_add_f32_e32 v190, v190, v191
	v_fma_f32 v190, v190, s82, v173
	v_rsq_f32_e32 v218, v190
	s_nop 0
	v_pk_mul_f32 v[112:113], v[112:113], v[218:219] op_sel_hi:[1,0]
	v_pk_mul_f32 v[114:115], v[114:115], v[218:219] op_sel_hi:[1,0]
	v_pk_mul_f32 v[116:117], v[116:117], v[218:219] op_sel_hi:[1,0]
	v_pk_mul_f32 v[118:119], v[118:119], v[218:219] op_sel_hi:[1,0]
	v_pk_mul_f32 v[120:121], v[120:121], v[218:219] op_sel_hi:[1,0]
	v_pk_mul_f32 v[122:123], v[122:123], v[218:219] op_sel_hi:[1,0]
	v_pk_mul_f32 v[124:125], v[124:125], v[218:219] op_sel_hi:[1,0]
	v_pk_mul_f32 v[126:127], v[126:127], v[218:219] op_sel_hi:[1,0]
	v_cvt_pk_bf16_f32 v242, v124, v125
	v_cvt_pk_bf16_f32 v243, v126, v127
	v_cvt_pk_bf16_f32 v244, v120, v121
	v_cvt_pk_bf16_f32 v245, v122, v123
	v_cvt_pk_bf16_f32 v246, v116, v117
	v_cvt_pk_bf16_f32 v247, v118, v119
	v_cvt_pk_bf16_f32 v248, v112, v113
	v_cvt_pk_bf16_f32 v249, v114, v115
	v_add_u32_e32 v250, 0x14000, v179
	global_store_dwordx4 v250, v[242:245], s[100:101]
	global_store_dwordx4 v250, v[246:249], s[100:101] offset:64
	v_add_f32_e32 v194, v194, v195
	v_add_f32_e32 v196, v196, v197
	v_add_f32_e32 v194, v194, v196
	v_mov_b32_e32 v195, v194
	s_nop 1
	v_permlane16_swap_b32_e32 v194, v195
	v_add_f32_e32 v194, v194, v195
	v_mov_b32_e32 v195, v194
	s_nop 1
	v_permlane32_swap_b32_e32 v194, v195
	v_add_f32_e32 v194, v194, v195
	v_fma_f32 v194, v194, s82, v173
	v_rsq_f32_e32 v218, v194
	s_nop 0
	v_pk_mul_f32 v[96:97], v[96:97], v[218:219] op_sel_hi:[1,0]
	v_pk_mul_f32 v[98:99], v[98:99], v[218:219] op_sel_hi:[1,0]
	v_pk_mul_f32 v[100:101], v[100:101], v[218:219] op_sel_hi:[1,0]
	v_pk_mul_f32 v[102:103], v[102:103], v[218:219] op_sel_hi:[1,0]
	v_pk_mul_f32 v[104:105], v[104:105], v[218:219] op_sel_hi:[1,0]
	v_pk_mul_f32 v[106:107], v[106:107], v[218:219] op_sel_hi:[1,0]
	v_pk_mul_f32 v[108:109], v[108:109], v[218:219] op_sel_hi:[1,0]
	v_pk_mul_f32 v[110:111], v[110:111], v[218:219] op_sel_hi:[1,0]
	v_cvt_pk_bf16_f32 v242, v108, v109
	v_cvt_pk_bf16_f32 v243, v110, v111
	v_cvt_pk_bf16_f32 v244, v104, v105
	v_cvt_pk_bf16_f32 v245, v106, v107
	v_cvt_pk_bf16_f32 v246, v100, v101
	v_cvt_pk_bf16_f32 v247, v102, v103
	v_cvt_pk_bf16_f32 v248, v96, v97
	v_cvt_pk_bf16_f32 v249, v98, v99
	v_add_u32_e32 v250, 0x28000, v179
	global_store_dwordx4 v250, v[242:245], s[100:101]
	global_store_dwordx4 v250, v[246:249], s[100:101] offset:64
	v_add_f32_e32 v198, v198, v199
	v_add_f32_e32 v200, v200, v201
	v_add_f32_e32 v198, v198, v200
	v_mov_b32_e32 v199, v198
	s_nop 1
	v_permlane16_swap_b32_e32 v198, v199
	v_add_f32_e32 v198, v198, v199
	v_mov_b32_e32 v199, v198
	s_nop 1
	v_permlane32_swap_b32_e32 v198, v199
	v_add_f32_e32 v198, v198, v199
	v_fma_f32 v198, v198, s82, v173
	v_rsq_f32_e32 v218, v198
	s_nop 0
	v_pk_mul_f32 v[80:81], v[80:81], v[218:219] op_sel_hi:[1,0]
	v_pk_mul_f32 v[82:83], v[82:83], v[218:219] op_sel_hi:[1,0]
	v_pk_mul_f32 v[84:85], v[84:85], v[218:219] op_sel_hi:[1,0]
	v_pk_mul_f32 v[86:87], v[86:87], v[218:219] op_sel_hi:[1,0]
	v_pk_mul_f32 v[88:89], v[88:89], v[218:219] op_sel_hi:[1,0]
	v_pk_mul_f32 v[90:91], v[90:91], v[218:219] op_sel_hi:[1,0]
	v_pk_mul_f32 v[92:93], v[92:93], v[218:219] op_sel_hi:[1,0]
	v_pk_mul_f32 v[94:95], v[94:95], v[218:219] op_sel_hi:[1,0]
	v_cvt_pk_bf16_f32 v242, v92, v93
	v_cvt_pk_bf16_f32 v243, v94, v95
	v_cvt_pk_bf16_f32 v244, v88, v89
	v_cvt_pk_bf16_f32 v245, v90, v91
	v_cvt_pk_bf16_f32 v246, v84, v85
	v_cvt_pk_bf16_f32 v247, v86, v87
	v_cvt_pk_bf16_f32 v248, v80, v81
	v_cvt_pk_bf16_f32 v249, v82, v83
	v_add_u32_e32 v250, 0x3c000, v179
	global_store_dwordx4 v250, v[242:245], s[100:101]
	global_store_dwordx4 v250, v[246:249], s[100:101] offset:64
; __device__ __forceinline__ unsigned cvtpk(float lo, float hi) { f32x2 v = {lo, hi}; bf16x2_t b = __builtin_convertvector(v, bf16x2_t); return __builtin_bit_cast(unsigned, b); }
; #define PG8_BAR __builtin_amdgcn_s_barrier()
; template <class Epi, bool HALO>
; __device__ __forceinline__ void gemm_phase(LAS unsigned char* lds, const bf16_t* Ag, const bf16_t* Btg, const int K, const int nM, const int nN, const int G, const int cidx, const int wave_, const Epi& E) {
;     ...
;         if (wr == 0) PG8_BAR;
;         E(acc, cur, wr, wc, fr, fq);
;         if (!has_next) break;
; #pragma unroll
;         for (int a = 0; a < 2; ++a)
; #pragma unroll
;             for (int b = 0; b < 2; ++b)
; #pragma unroll
;                 for (int m = 0; m < 4; ++m)
; #pragma unroll
;                     for (int n = 0; n < 2; ++n) acc[a][b][m][n] = (f32x4){0.f, 0.f, 0.f, 0.f};
;         cur = nxt; cA = nA; cB = nB; ++ui;
;         if (wr == 1) PG8_BAR;
;     __device__ __forceinline__ void operator()(const f32x4 (&acc)[2][2][4][2], const Unit& u, int wr, int wc, int fr, int fq) const {
;     ...
;                 const int row = u.pm * BM + ai * HALF + wr * 64 + m * 16 + fr;
;                 float rs = 1.f;
;                 if (PS) { const f32x4 p = *(const f32x4*)(PS + (size_t)row * 16 + 4 * fq); float s = (p[0] + p[1]) + (p[2] + p[3]); s = bfly_add<16>(s); s = bfly_add<32>(s); rs = rsqrtf(s * (1.f / DM) + EPS); }
;                 f32x4 v[2][2]; float ss = 0.f;
; #pragma unroll
;                 for (int bj = 0; bj < 2; ++bj)
; #pragma unroll
;                     for (int n = 0; n < 2; ++n) { v[bj][n] = acc[ai][bj][m][n] * rs; const f32x4 x = v[bj][n]; ss += (x[0] * x[0] + x[1] * x[1]) + (x[2] * x[2] + x[3] * x[3]); }
;                 if (nrm) { ss = bfly_add<16>(ss); ss = bfly_add<32>(ss); const float r2 = rsqrtf(ss * (1.f / 64.f) + EPS);
; #pragma unroll
;                     for (int bj = 0; bj < 2; ++bj)
; #pragma unroll
;                         for (int n = 0; n < 2; ++n) v[bj][n] = v[bj][n] * r2 * gv[bj][n]; }
;                 bf16_t* rowp = Z + (size_t)row * ldz + u.pn * BM + 64 * wc + 8 * fq;
; #pragma unroll
;                 for (int bj = 0; bj < 2; ++bj) { u32x4 w; w.x = cvtpk(v[bj][0][0], v[bj][0][1]); w.y = cvtpk(v[bj][0][2], v[bj][0][3]); w.z = cvtpk(v[bj][1][0], v[bj][1][1]); w.w = cvtpk(v[bj][1][2], v[bj][1][3]);
;                     *(u32x4*)(rowp + 32 * bj) = w; }
	v_add_f32_e32 v202, v202, v203
	v_add_f32_e32 v204, v204, v205
	v_add_f32_e32 v202, v202, v204
	v_mov_b32_e32 v203, v202
	s_nop 1
	v_permlane16_swap_b32_e32 v202, v203
	v_add_f32_e32 v202, v202, v203
	v_mov_b32_e32 v203, v202
	s_nop 1
	v_permlane32_swap_b32_e32 v202, v203
	v_add_f32_e32 v202, v202, v203
	v_fma_f32 v202, v202, s82, v173
	v_rsq_f32_e32 v218, v202
	s_nop 0
	v_pk_mul_f32 v[48:49], v[48:49], v[218:219] op_sel_hi:[1,0]
	v_pk_mul_f32 v[50:51], v[50:51], v[218:219] op_sel_hi:[1,0]
	v_pk_mul_f32 v[52:53], v[52:53], v[218:219] op_sel_hi:[1,0]
	v_pk_mul_f32 v[54:55], v[54:55], v[218:219] op_sel_hi:[1,0]
	v_pk_mul_f32 v[56:57], v[56:57], v[218:219] op_sel_hi:[1,0]
	v_pk_mul_f32 v[58:59], v[58:59], v[218:219] op_sel_hi:[1,0]
	v_pk_mul_f32 v[60:61], v[60:61], v[218:219] op_sel_hi:[1,0]
	v_pk_mul_f32 v[62:63], v[62:63], v[218:219] op_sel_hi:[1,0]
	v_cvt_pk_bf16_f32 v242, v60, v61
	v_cvt_pk_bf16_f32 v243, v62, v63
	v_cvt_pk_bf16_f32 v244, v56, v57
	v_cvt_pk_bf16_f32 v245, v58, v59
	v_cvt_pk_bf16_f32 v246, v52, v53
	v_cvt_pk_bf16_f32 v247, v54, v55
	v_cvt_pk_bf16_f32 v248, v48, v49
	v_cvt_pk_bf16_f32 v249, v50, v51
	v_add_u32_e32 v250, 0xa0000, v179
	global_store_dwordx4 v250, v[242:245], s[100:101]
	global_store_dwordx4 v250, v[246:249], s[100:101] offset:64
	v_add_f32_e32 v206, v206, v207
	v_add_f32_e32 v208, v208, v209
	v_add_f32_e32 v206, v206, v208
	v_mov_b32_e32 v207, v206
	s_nop 1
	v_permlane16_swap_b32_e32 v206, v207
	v_add_f32_e32 v206, v206, v207
	v_mov_b32_e32 v207, v206
	s_nop 1
	v_permlane32_swap_b32_e32 v206, v207
	v_add_f32_e32 v206, v206, v207
	v_fma_f32 v206, v206, s82, v173
	v_rsq_f32_e32 v218, v206
	s_nop 0
	v_pk_mul_f32 v[32:33], v[32:33], v[218:219] op_sel_hi:[1,0]
	v_pk_mul_f32 v[34:35], v[34:35], v[218:219] op_sel_hi:[1,0]
	v_pk_mul_f32 v[36:37], v[36:37], v[218:219] op_sel_hi:[1,0]
	v_pk_mul_f32 v[38:39], v[38:39], v[218:219] op_sel_hi:[1,0]
	v_pk_mul_f32 v[40:41], v[40:41], v[218:219] op_sel_hi:[1,0]
	v_pk_mul_f32 v[42:43], v[42:43], v[218:219] op_sel_hi:[1,0]
	v_pk_mul_f32 v[44:45], v[44:45], v[218:219] op_sel_hi:[1,0]
	v_pk_mul_f32 v[46:47], v[46:47], v[218:219] op_sel_hi:[1,0]
	v_cvt_pk_bf16_f32 v242, v44, v45
	v_cvt_pk_bf16_f32 v243, v46, v47
	v_cvt_pk_bf16_f32 v244, v40, v41
	v_cvt_pk_bf16_f32 v245, v42, v43
	v_cvt_pk_bf16_f32 v246, v36, v37
	v_cvt_pk_bf16_f32 v247, v38, v39
	v_cvt_pk_bf16_f32 v248, v32, v33
	v_cvt_pk_bf16_f32 v249, v34, v35
	v_add_u32_e32 v250, 0xb4000, v179
	global_store_dwordx4 v250, v[242:245], s[100:101]
	global_store_dwordx4 v250, v[246:249], s[100:101] offset:64
	v_add_f32_e32 v210, v210, v211
	v_add_f32_e32 v212, v212, v213
	v_add_f32_e32 v210, v210, v212
	v_mov_b32_e32 v211, v210
	s_nop 1
	v_permlane16_swap_b32_e32 v210, v211
	v_add_f32_e32 v210, v210, v211
	v_mov_b32_e32 v211, v210
	s_nop 1
	v_permlane32_swap_b32_e32 v210, v211
	v_add_f32_e32 v210, v210, v211
	v_fma_f32 v210, v210, s82, v173
	v_rsq_f32_e32 v218, v210
	s_nop 0
	v_pk_mul_f32 v[16:17], v[16:17], v[218:219] op_sel_hi:[1,0]
	v_pk_mul_f32 v[18:19], v[18:19], v[218:219] op_sel_hi:[1,0]
	v_pk_mul_f32 v[20:21], v[20:21], v[218:219] op_sel_hi:[1,0]
	v_pk_mul_f32 v[22:23], v[22:23], v[218:219] op_sel_hi:[1,0]
	v_pk_mul_f32 v[24:25], v[24:25], v[218:219] op_sel_hi:[1,0]
	v_pk_mul_f32 v[26:27], v[26:27], v[218:219] op_sel_hi:[1,0]
	v_pk_mul_f32 v[28:29], v[28:29], v[218:219] op_sel_hi:[1,0]
	v_pk_mul_f32 v[30:31], v[30:31], v[218:219] op_sel_hi:[1,0]
	v_cvt_pk_bf16_f32 v242, v28, v29
	v_cvt_pk_bf16_f32 v243, v30, v31
	v_cvt_pk_bf16_f32 v244, v24, v25
	v_cvt_pk_bf16_f32 v245, v26, v27
	v_cvt_pk_bf16_f32 v246, v20, v21
	v_cvt_pk_bf16_f32 v247, v22, v23
	v_cvt_pk_bf16_f32 v248, v16, v17
	v_cvt_pk_bf16_f32 v249, v18, v19
	v_add_u32_e32 v250, 0xc8000, v179
	global_store_dwordx4 v250, v[242:245], s[100:101]
	global_store_dwordx4 v250, v[246:249], s[100:101] offset:64
	v_add_f32_e32 v214, v214, v215
	v_add_f32_e32 v216, v216, v217
	v_add_f32_e32 v214, v214, v216
	v_mov_b32_e32 v215, v214
	s_nop 1
	v_permlane16_swap_b32_e32 v214, v215
	v_add_f32_e32 v214, v214, v215
	v_mov_b32_e32 v215, v214
	s_nop 1
	v_permlane32_swap_b32_e32 v214, v215
	v_add_f32_e32 v214, v214, v215
	v_fma_f32 v214, v214, s82, v173
	v_rsq_f32_e32 v218, v214
	s_nop 0
	v_pk_mul_f32 v[0:1], v[0:1], v[218:219] op_sel_hi:[1,0]
	v_pk_mul_f32 v[2:3], v[2:3], v[218:219] op_sel_hi:[1,0]
	v_pk_mul_f32 v[4:5], v[4:5], v[218:219] op_sel_hi:[1,0]
	v_pk_mul_f32 v[6:7], v[6:7], v[218:219] op_sel_hi:[1,0]
	v_pk_mul_f32 v[8:9], v[8:9], v[218:219] op_sel_hi:[1,0]
	v_pk_mul_f32 v[10:11], v[10:11], v[218:219] op_sel_hi:[1,0]
	v_pk_mul_f32 v[12:13], v[12:13], v[218:219] op_sel_hi:[1,0]
	v_pk_mul_f32 v[14:15], v[14:15], v[218:219] op_sel_hi:[1,0]
	v_cvt_pk_bf16_f32 v242, v12, v13
	v_cvt_pk_bf16_f32 v243, v14, v15
	v_cvt_pk_bf16_f32 v244, v8, v9
	v_cvt_pk_bf16_f32 v245, v10, v11
	v_cvt_pk_bf16_f32 v246, v4, v5
	v_cvt_pk_bf16_f32 v247, v6, v7
	v_cvt_pk_bf16_f32 v248, v0, v1
	v_cvt_pk_bf16_f32 v249, v2, v3
	v_add_u32_e32 v250, 0xdc000, v179
	global_store_dwordx4 v250, v[242:245], s[100:101]
	global_store_dwordx4 v250, v[246:249], s[100:101] offset:64
EZ2_done:
	s_andn2_b64 vcc, exec, s[6:7]
	s_mov_b64 s[4:5], -1
	s_cbranch_vccnz .LBB0_145
	s_andn2_b64 vcc, exec, s[12:13]
	s_cbranch_vccnz .LBB0_144
	s_barrier
	s_branch .LBB0_144
